# v9 + prompt dilated-attention inner loop: all 8 K-fragment ds_reads issued up front; 6 of 8 V^T fragment reads issued right after QK (counted lgkmcnt)
# speedup vs baseline: 1.0046x; 1.0044x over previous
; #define LAS __attribute__((address_space(3)))
; __global__ void __launch_bounds__(512, 2) mega_fwd(Args args) {
;     ...
;                 for (int kb = kb0; kb < kb1; ++kb) {
;                     f32x16 sacc;
; #pragma unroll
;                     for (int r = 0; r < 16; ++r) sacc[r] = 0.f;
; #pragma unroll
;                     for (int s2 = 0; s2 < 8; ++s2) sacc = __builtin_amdgcn_mfma_f32_32x32x16_bf16(*(const LAS bf16x8*)(kp + kb * 32 * VP + s2 * 32), qf[s2], sacc, 0, 0, 0);
;     ...
;                     for (int mb = 0; mb < 4; ++mb)
; #pragma unroll
;                         for (int st = 0; st < 2; ++st) {
;                             const s16x4 lo = __builtin_amdgcn_ds_read_tr16_b64_v4i16((LAS s16x4*)(trb + (kb * 32 + 16 * st) * VP + 64 * mb));
;                             const s16x4 hi = __builtin_amdgcn_ds_read_tr16_b64_v4i16((LAS s16x4*)(trb + (kb * 32 + 16 * st + 8) * VP + 64 * mb));
.LBB0_432:
	v_add_u32_e32 v1, s46, v203
	ds_read_b128 v[2:5], v1
	ds_read_b128 v[6:9], v1 offset:32
	ds_read_b128 v[228:231], v1 offset:64
	ds_read_b128 v[232:235], v1 offset:96
	ds_read_b128 v[236:239], v1 offset:128
	ds_read_b128 v[240:243], v1 offset:160
	ds_read_b128 v[244:247], v1 offset:192
	ds_read_b128 v[248:251], v1 offset:224
	s_and_b32 s16, s58, 0x7ffffffb
	s_cmp_eq_u32 s16, 0
	s_cselect_b64 s[6:7], -1, 0
	s_waitcnt vmcnt(1) lgkmcnt(7)
	v_mfma_f32_32x32x16_bf16 v[80:95], v[2:5], v[132:135], 0
	s_cmp_lg_u32 s16, 0
	s_waitcnt lgkmcnt(6)
	v_mfma_f32_32x32x16_bf16 v[80:95], v[6:9], v[124:127], v[80:95]
	s_waitcnt lgkmcnt(5)
	v_mfma_f32_32x32x16_bf16 v[80:95], v[228:231], v[128:131], v[80:95]
	s_waitcnt lgkmcnt(4)
	v_mfma_f32_32x32x16_bf16 v[80:95], v[232:235], v[136:139], v[80:95]
	s_waitcnt lgkmcnt(3)
	v_mfma_f32_32x32x16_bf16 v[80:95], v[236:239], v[140:143], v[80:95]
	s_waitcnt lgkmcnt(2)
	v_mfma_f32_32x32x16_bf16 v[80:95], v[240:243], v[144:147], v[80:95]
	s_waitcnt lgkmcnt(1)
	v_mfma_f32_32x32x16_bf16 v[80:95], v[244:247], v[148:151], v[80:95]
	s_waitcnt vmcnt(0) lgkmcnt(0)
	v_mfma_f32_32x32x16_bf16 v[80:95], v[248:251], v[152:155], v[80:95]
	v_add_u32_e32 v227, s46, v205
	v_add_u32_e32 v227, 0x11000, v227
	ds_read_b64_tr_b16 v[228:229], v227
	ds_read_b64_tr_b16 v[230:231], v227 offset:2176
	ds_read_b64_tr_b16 v[232:233], v227 offset:4352
	ds_read_b64_tr_b16 v[234:235], v227 offset:6528
	ds_read_b64_tr_b16 v[236:237], v227 offset:64
	ds_read_b64_tr_b16 v[238:239], v227 offset:2240
	ds_read_b64_tr_b16 v[240:241], v227 offset:4416
	ds_read_b64_tr_b16 v[242:243], v227 offset:6592
	ds_read_b64_tr_b16 v[244:245], v227 offset:128
	ds_read_b64_tr_b16 v[246:247], v227 offset:2304
	ds_read_b64_tr_b16 v[248:249], v227 offset:4480
	ds_read_b64_tr_b16 v[250:251], v227 offset:6656
	s_cbranch_scc0 .LBB0_434
	s_lshl_b32 s6, s58, s35
	s_lshl_b32 s6, s6, 5
	s_add_i32 s6, s6, s8
	s_cmp_lt_i32 s6, 0
	s_cselect_b64 s[6:7], -1, 0

; #define LAS __attribute__((address_space(3)))
; __device__ __forceinline__ unsigned pk2(float lo, float hi) { f32x2_t v = {lo, hi}; bf16x2_t b = __builtin_convertvector(v, bf16x2_t); return __builtin_bit_cast(unsigned, b); }
; __global__ void __launch_bounds__(512, 2) mega_fwd(Args args) {
;     ...
;                     const float mn = fmaxf(m, mx * SCALE_LOG2), alpha = __builtin_amdgcn_exp2f(m - mn); m = mn;
;                     float ls = 0.f;
; #pragma unroll
;                     for (int r = 0; r < 16; ++r) { const float p = __builtin_amdgcn_exp2f(__builtin_fmaf(sacc[r], SCALE_LOG2, -mn)); ls += p; sacc[r] = p; }
;                     l = l * alpha + ls;
;                     if (__builtin_amdgcn_ballot_w64(alpha != 1.f) != 0ull) {
; #pragma unroll
;                         for (int mb = 0; mb < 4; ++mb)
; #pragma unroll
;                             for (int r = 0; r < 16; ++r) o[mb][r] *= alpha;
;                     }
;                     bf16x8 pf[2];
; #pragma unroll
;                     for (int st = 0; st < 2; ++st) { u32x4 w; w.x = pk2(sacc[8 * st + 0], sacc[8 * st + 1]); w.y = pk2(sacc[8 * st + 2], sacc[8 * st + 3]); w.z = pk2(sacc[8 * st + 4], sacc[8 * st + 5]); w.w = pk2(sacc[8 * st + 6], sacc[8 * st + 7]);
;                         pf[st] = __builtin_bit_cast(bf16x8, w); }
; #pragma unroll
;                     for (int mb = 0; mb < 4; ++mb)
; #pragma unroll
;                         for (int st = 0; st < 2; ++st) {
;                             const s16x4 lo = __builtin_amdgcn_ds_read_tr16_b64_v4i16((LAS s16x4*)(trb + (kb * 32 + 16 * st) * VP + 64 * mb));
;                             const s16x4 hi = __builtin_amdgcn_ds_read_tr16_b64_v4i16((LAS s16x4*)(trb + (kb * 32 + 16 * st + 8) * VP + 64 * mb));
;                             const bf16x8 a = __builtin_shufflevector(lo, hi, 0, 1, 2, 3, 4, 5, 6, 7);
;                             o[mb] = __builtin_amdgcn_mfma_f32_32x32x16_bf16(a, pf[st], o[mb], 0, 0, 0); }
.LBB0_438:
	v_fma_f32 v4, v81, s49, -v3
	v_exp_f32_e32 v223, v4
	v_fma_f32 v4, v82, s49, -v3
	v_exp_f32_e32 v224, v4
	v_fma_f32 v4, v83, s49, -v3
	v_exp_f32_e32 v225, v4
	v_fma_f32 v4, v84, s49, -v3
	v_exp_f32_e32 v84, v4
	v_fma_f32 v4, v85, s49, -v3
	v_exp_f32_e32 v85, v4
	v_fma_f32 v4, v86, s49, -v3
	v_exp_f32_e32 v86, v4
	v_fma_f32 v4, v87, s49, -v3
	v_exp_f32_e32 v87, v4
	v_fma_f32 v4, v88, s49, -v3
	v_exp_f32_e32 v88, v4
	v_fma_f32 v4, v89, s49, -v3
	v_exp_f32_e32 v89, v4
	v_fma_f32 v4, v90, s49, -v3
	v_exp_f32_e32 v90, v4
	v_fma_f32 v4, v91, s49, -v3
	v_exp_f32_e32 v91, v4
	v_fma_f32 v4, v92, s49, -v3
	v_fma_f32 v1, v80, s49, -v3
	v_exp_f32_e32 v92, v4
	v_fma_f32 v4, v93, s49, -v3
	v_fma_f32 v80, v94, s49, -v3
	v_exp_f32_e32 v93, v4
	v_exp_f32_e32 v1, v1
	ds_read_b64_tr_b16 v[12:13], v227 offset:192
	ds_read_b64_tr_b16 v[14:15], v227 offset:2368
	v_cvt_pk_bf16_f32 v9, v224, v225
	v_cvt_pk_bf16_f32 v10, v84, v85
	v_cvt_pk_bf16_f32 v8, v1, v223
	v_cvt_pk_bf16_f32 v11, v86, v87
	v_fma_f32 v4, v95, s49, -v3
	v_exp_f32_e32 v226, v80
	v_mfma_f32_32x32x16_bf16 v[64:79], v[228:231], v[8:11], v[64:79]
	v_exp_f32_e32 v95, v4
	ds_read_b64_tr_b16 v[80:81], v227 offset:4544
	ds_read_b64_tr_b16 v[82:83], v227 offset:6720
	v_cvt_pk_bf16_f32 v4, v88, v89
	v_cvt_pk_bf16_f32 v5, v90, v91
	v_cvt_pk_bf16_f32 v6, v92, v93
	v_cvt_pk_bf16_f32 v7, v226, v95
	v_mfma_f32_32x32x16_bf16 v[48:63], v[236:239], v[8:11], v[48:63]
	v_add_f32_e32 v1, 0, v1
	v_add_f32_e32 v1, v1, v223
	v_add_f32_e32 v1, v1, v224
	v_mfma_f32_32x32x16_bf16 v[64:79], v[232:235], v[4:7], v[64:79]
	v_add_f32_e32 v1, v1, v225
	v_add_f32_e32 v1, v1, v84
	v_add_f32_e32 v1, v1, v85
	v_add_f32_e32 v1, v1, v86
	v_mfma_f32_32x32x16_bf16 v[48:63], v[240:243], v[4:7], v[48:63]
	v_add_f32_e32 v1, v1, v87
	v_add_f32_e32 v1, v1, v88
	v_add_f32_e32 v1, v1, v89
	v_add_f32_e32 v1, v1, v90
	v_mfma_f32_32x32x16_bf16 v[32:47], v[244:247], v[8:11], v[32:47]
	v_add_f32_e32 v1, v1, v91
	v_add_f32_e32 v1, v1, v92
	v_add_f32_e32 v1, v1, v93
	v_add_f32_e32 v1, v1, v226
	s_waitcnt lgkmcnt(2)
	v_mfma_f32_32x32x16_bf16 v[16:31], v[12:15], v[8:11], v[16:31]
	v_add_f32_e32 v1, v1, v95
	s_add_i32 s58, s58, 1
	v_fmac_f32_e32 v1, v222, v2
	v_add_u32_e32 v221, 32, v221
	v_subrev_u32_e32 v220, 32, v220
	v_add_u32_e32 v205, 0x2200, v205
	s_cmp_ge_u32 s58, s45
	v_mfma_f32_32x32x16_bf16 v[32:47], v[248:251], v[4:7], v[32:47]
	v_add_u32_e32 v203, 0x2200, v203
	s_waitcnt lgkmcnt(0)
	v_mfma_f32_32x32x16_bf16 v[16:31], v[80:83], v[4:7], v[16:31]
	s_cbranch_scc1 .LBB0_440
	v_mov_b32_e32 v222, v1
	v_mov_b32_e32 v223, v3
	s_branch .LBB0_432
